# Y-GEMM's final drain wait and barrier moved behind the attention setup and entry prefetch (store acks and setup overlap the first K/V/Q loads)
# speedup vs baseline: 1.0000x; 1.0000x over previous
; __device__ __forceinline__ void attn_phase(LAS unsigned char* lds, int vcu, int G, const bf16* Qp, const bf16* Kp, const bf16* Vt, const float* sinks, bf16* AO, int ldo, float* st) {
;     ...
;     int tid = threadIdx.x; asm volatile("" : "+v"(tid));
;     const int lane = tid & 63, wave = __builtin_amdgcn_readfirstlane(tid >> 6), r32 = lane & 31, hi = lane >> 5, hq = wave & 3, qsub = wave >> 2;
;     const float NEG = -INFINITY;
;     float ssq_acc = 0.f;
;     for (int it = 0; it < 4; ++it) { const int id = ((vcu >> 5) << 7) | (it << 5) | (vcu & 31);
;         const int b = id >> 7, kvh = (id >> 5) & 3, q0 = 64 * (id & 31), h = kvh * 4 + hq;
;         const size_t tok0 = (size_t)b * SEQ;
;         const int jt0 = (q0 >= 128) ? 0 : (128 - q0) / 32;
;         v4u kv[3], vv[3];
; #pragma unroll
;         for (int i = 0; i < 3; ++i) { const int c = tid + 512 * i, row = c >> 3, ch = c & 7, key = q0 - 128 + row;
;             if (key >= 0) kv[i] = *(const v4u*)(Kp + (tok0 + key) * D_KV + kvh * HD + ch * 8); }
; #pragma unroll
;         for (int i = 0; i < 3; ++i) { const int c = tid + 512 * i, d = c / 24, ch = c - d * 24, key0 = q0 - 128 + 8 * ch;
;             if (key0 >= 0) vv[i] = *(const v4u*)(Vt + (size_t)(kvh * HD + d) * M + tok0 + key0); }
;         const bf16* qrow = Qp + (tok0 + q0 + 32 * qsub + r32) * D_ATTN + h * HD + 32 * hi;
.LBB0_653:
.LBB0_654:
	v_writelane_b32 v254, s88, 53
	v_mov_b32_e32 v4, v0
	s_mov_b32 s15, 0x2aaaaaab
	v_writelane_b32 v254, s89, 54
	v_writelane_b32 v254, s2, 55
	v_readfirstlane_b32 s68, v4
	s_lshr_b32 s0, s68, 6
	v_writelane_b32 v254, s3, 56
	v_writelane_b32 v254, s0, 57
	s_lshl_b32 s0, s90, 6
	v_mul_hi_i32 v9, v4, s15
	s_bfe_i32 s66, s90, 0x190005
	s_and_b32 s3, s0, 0x7c0
	v_add_u32_e32 v8, 0x200, v4
	v_lshrrev_b32_e32 v13, 31, v9
	v_ashrrev_i32_e32 v9, 2, v9
	s_ashr_i32 s67, s66, 31
	v_mov_b32_e32 v3, s3
	s_sub_i32 s0, 0x80, s3
	v_add_u32_e32 v16, v9, v13
	v_mul_hi_i32 v9, v8, s15
	s_ashr_i32 s2, s68, 8
	s_lshl_b64 s[62:63], s[66:67], 11
	v_sub_co_u32_e32 v3, vcc, 0x7f, v3
	s_lshr_b32 s4, s0, 5
	v_lshrrev_b32_e32 v13, 31, v9
	v_ashrrev_i32_e32 v9, 2, v9
	s_and_b64 s[0:1], vcc, exec
	s_movk_i32 s16, 0xffe8
	v_add_u32_e32 v22, v9, v13
	s_cselect_b32 s28, 0, s4
	v_ashrrev_i32_e32 v25, 3, v8
	v_mad_u64_u32 v[8:9], s[4:5], v22, s16, v[8:9]
	s_add_i32 s14, s3, 0xffffff80
	v_lshlrev_b32_e32 v9, 3, v8
	v_add_u32_e32 v12, 0x400, v4
	v_add_u32_e32 v13, s14, v9
	v_cmp_lt_i32_e64 s[12:13], -1, v13
	v_mul_hi_i32 v13, v12, s15
	v_bfe_u32 v141, v4, 5, 1
	v_lshlrev_b32_e32 v5, 4, v4
	v_lshrrev_b32_e32 v24, 31, v13
	v_ashrrev_i32_e32 v13, 2, v13
	s_lshl_b32 s76, s2, 5
	v_and_b32_e32 v26, 0x70, v5
	v_lshlrev_b32_e32 v5, 2, v141
	v_add_u32_e32 v24, v13, v24
	s_ashr_i32 s77, s76, 31
	v_ashrrev_i32_e32 v30, 3, v12
	v_mad_u64_u32 v[18:19], s[4:5], v16, s16, v[4:5]
	v_mad_u64_u32 v[12:13], s[4:5], v24, s16, v[12:13]
	v_ashrrev_i32_e32 v23, 3, v4
	v_lshlrev_b32_e32 v19, 3, v18
	v_lshlrev_b32_e32 v13, 3, v12
	s_movk_i32 s5, 0x188
	s_cmp_ge_i32 s2, s28
	v_add_u32_e32 v20, s14, v19
	v_cmp_gt_i32_e64 s[16:17], v23, v3
	v_cmp_gt_i32_e64 s[18:19], v25, v3
	v_cmp_gt_i32_e64 s[20:21], v30, v3
	v_cmp_gt_i32_e64 s[22:23], v19, v3
	v_mul_lo_u32 v19, v16, s5
	v_cmp_gt_i32_e64 s[24:25], v9, v3
	v_mul_lo_u32 v9, v22, s5
	v_cmp_gt_i32_e64 s[26:27], v13, v3
	v_mul_lo_u32 v3, v24, s5
	s_cselect_b64 s[82:83], -1, 0
	s_add_i32 s5, s2, 1
	s_cmp_ge_i32 s5, s28
	v_and_b32_e32 v140, 31, v4
	s_cselect_b64 s[72:73], -1, 0
	s_add_i32 s60, s2, 2
	s_movk_i32 s4, 0x90
	v_lshlrev_b32_e32 v34, 4, v8
	v_or_b32_e32 v8, s76, v140
	s_cmp_ge_i32 s60, s28
	v_mul_lo_u32 v36, v8, s4
	v_lshl_or_b32 v8, s5, 5, v140
	s_cselect_b64 s[88:89], -1, 0
	s_add_i32 s69, s2, 3
	v_mul_lo_u32 v37, v8, s4
	v_lshl_or_b32 v8, s60, 5, v140
	s_cmp_ge_i32 s69, s28
	v_mul_lo_u32 v38, v8, s4
	s_cselect_b64 s[96:97], -1, 0
	v_lshl_or_b32 v8, s69, 5, v140
	s_add_i32 s70, s2, 4
	v_mul_lo_u32 v39, v8, s4
	v_lshl_or_b32 v8, s70, 5, v140
	v_mul_lo_u32 v40, v8, s4
	v_or_b32_e32 v8, 2, v5
	v_cmp_gt_u32_e64 s[34:35], v8, v140
	v_or_b32_e32 v8, 3, v5
	v_cmp_gt_u32_e64 s[36:37], v8, v140
	v_or_b32_e32 v8, 8, v5
	v_cmp_gt_u32_e64 s[38:39], v8, v140
	v_or_b32_e32 v8, 9, v5
	v_cmp_gt_u32_e64 s[40:41], v8, v140
	v_or_b32_e32 v8, 10, v5
	v_cmp_gt_u32_e64 s[42:43], v8, v140
	v_or_b32_e32 v8, 11, v5
	v_cmp_gt_u32_e64 s[44:45], v8, v140
	v_or_b32_e32 v8, 16, v5
	v_cmp_gt_u32_e64 s[46:47], v8, v140
	v_or_b32_e32 v8, 17, v5
	v_cmp_gt_u32_e64 s[48:49], v8, v140
	v_or_b32_e32 v8, 18, v5
	v_lshlrev_b32_e32 v28, 6, v141
	v_cmp_gt_u32_e64 s[50:51], v8, v140
	v_or_b32_e32 v8, 19, v5
	v_add_u32_e32 v29, 0, v28
	s_movk_i32 s0, 0xffc8
	v_cmp_gt_u32_e64 s[52:53], v8, v140
	v_or_b32_e32 v8, 24, v5
	v_mad_i32_i24 v17, v141, s0, v29
	v_add_u32_e32 v31, s14, v13
	v_cmp_gt_u32_e64 s[54:55], v8, v140
	v_or_b32_e32 v8, 25, v5
	v_add_u32_e32 v6, s14, v23
	v_add_u32_e32 v10, s14, v25
	v_add_u32_e32 v14, s14, v30
	v_cmp_lt_i32_e64 s[14:15], -1, v31
	v_mul_lo_u32 v31, v23, s4
	v_mul_lo_u32 v32, v25, s4
	s_cmp_ge_i32 s70, s28
	v_cmp_gt_u32_e64 s[56:57], v8, v140
	v_or_b32_e32 v8, 26, v5
	v_lshl_add_u32 v41, s5, 6, v17
	v_lshl_add_u32 v42, s60, 6, v17
	v_lshl_add_u32 v43, s2, 6, v17
	v_lshl_add_u32 v45, s69, 6, v17
	v_lshl_add_u32 v46, s70, 6, v17
	v_ashrrev_i32_e32 v17, 31, v16
	v_ashrrev_i32_e32 v23, 31, v22
	v_ashrrev_i32_e32 v25, 31, v24
	v_mul_lo_u32 v30, v30, s4
	v_add_u32_e32 v33, 0, v9
	v_lshlrev_b32_e32 v35, 4, v12
	s_cselect_b64 s[74:75], -1, 0
	v_cmp_gt_u32_e64 s[58:59], v8, v140
	v_lshlrev_b64 v[8:9], 15, v[16:17]
	s_lshl_b64 s[4:5], s[66:67], 12
	v_lshlrev_b64 v[12:13], 15, v[22:23]
	v_lshlrev_b64 v[16:17], 15, v[24:25]
	v_mov_b32_e32 v21, v2
	v_cmp_gt_u32_e64 s[28:29], v5, v140
	v_cmp_lt_u32_e64 s[30:31], v5, v140
; __device__ __forceinline__ void attn_phase(LAS unsigned char* lds, int vcu, int G, const bf16* Qp, const bf16* Kp, const bf16* Vt, const float* sinks, bf16* AO, int ldo, float* st) {
;     ...
;         v4u kv[3], vv[3];
; #pragma unroll
;         for (int i = 0; i < 3; ++i) { const int c = tid + 512 * i, row = c >> 3, ch = c & 7, key = q0 - 128 + row;
;             if (key >= 0) kv[i] = *(const v4u*)(Kp + (tok0 + key) * D_KV + kvh * HD + ch * 8); }
; #pragma unroll
;         for (int i = 0; i < 3; ++i) { const int c = tid + 512 * i, d = c / 24, ch = c - d * 24, key0 = q0 - 128 + 8 * ch;
;             if (key0 >= 0) vv[i] = *(const v4u*)(Vt + (size_t)(kvh * HD + d) * M + tok0 + key0); }
;         const bf16* qrow = Qp + (tok0 + q0 + 32 * qsub + r32) * D_ATTN + h * HD + 32 * hi;
;         bf16x8 qf[4];
; #pragma unroll
;         for (int kk = 0; kk < 4; ++kk) qf[kk] = *(const bf16x8*)(qrow + 8 * kk);
;     ...
;         const float sk = sinks[h] * 1.4426950408889634f;
	v_or_b32_e32 v5, 27, v5
	v_lshl_add_u64 v[8:9], v[8:9], 0, s[4:5]
	v_lshl_add_u64 v[12:13], v[12:13], 0, s[4:5]
	v_lshl_add_u64 v[16:17], v[16:17], 0, s[4:5]
	s_movk_i32 s4, 0xc0
	v_cmp_lt_i32_e64 s[10:11], -1, v20
	v_cmp_gt_u32_e64 s[60:61], v5, v140
	v_lshl_add_u64 v[8:9], v[20:21], 1, v[8:9]
	v_mul_lo_u32 v5, v22, s4
	v_mul_lo_u32 v20, v24, s4
	s_mov_b64 s[4:5], 0xd800000
	v_lshl_add_u64 v[124:125], v[8:9], 0, s[4:5]
	v_lshl_add_u32 v8, v4, 3, s3
	v_sub_u32_e32 v4, v8, v5
	v_add_u32_e32 v4, 0xf80, v4
	v_mov_b32_e32 v5, v2
	v_lshl_add_u64 v[4:5], v[4:5], 1, v[12:13]
	v_lshl_add_u64 v[126:127], v[4:5], 0, s[4:5]
	v_sub_u32_e32 v4, v8, v20
	v_add_u32_e32 v4, 0x1f80, v4
	v_mov_b32_e32 v5, v2
	v_mov_b32_e32 v7, v2
	v_lshl_add_u64 v[4:5], v[4:5], 1, v[16:17]
	v_lshl_add_u64 v[128:129], v[4:5], 0, s[4:5]
	s_lshl_b64 s[4:5], s[66:67], 20
	v_lshlrev_b64 v[4:5], 9, v[6:7]
	v_lshl_add_u64 v[4:5], s[4:5], 0, v[4:5]
	v_mov_b32_e32 v11, v2
	v_or_b32_e32 v4, v4, v26
	s_mov_b64 s[66:67], 0xd000000
	v_lshl_add_u64 v[130:131], v[4:5], 0, s[66:67]
	v_lshlrev_b64 v[4:5], 9, v[10:11]
	v_lshl_add_u64 v[4:5], s[4:5], 0, v[4:5]
	v_mov_b32_e32 v15, v2
	v_or_b32_e32 v4, v4, v26
	v_lshl_add_u64 v[132:133], v[4:5], 0, s[66:67]
	v_lshlrev_b64 v[4:5], 9, v[14:15]
	v_lshl_add_u64 v[4:5], s[4:5], 0, v[4:5]
	s_lshr_b32 s4, s68, 4
	s_and_b32 s4, s4, 12
	s_add_u32 s4, s64, s4
	s_addc_u32 s5, s65, 0
	v_writelane_b32 v254, s90, 58
	v_or_b32_e32 v4, v4, v26
	s_add_u32 s62, s62, s76
	v_lshl_add_u64 v[134:135], v[4:5], 0, s[66:67]
	v_writelane_b32 v254, s76, 59
	s_addc_u32 s63, s63, s77
	v_or_b32_e32 v4, s3, v140
	v_mov_b32_e32 v5, v2
	v_lshl_add_u64 v[4:5], s[62:63], 0, v[4:5]
	s_lshl_b32 s62, s68, 1
	v_cmp_lt_i32_e64 s[0:1], -1, v6
	v_lshlrev_b64 v[6:7], 12, v[4:5]
	s_and_b32 s64, s62, 0x180
	v_lshlrev_b32_e32 v8, 3, v141
	v_or3_b32 v6, v6, s64, v8
	s_mov_b64 s[62:63], 0xf000040
	v_lshlrev_b64 v[4:5], 11, v[4:5]
	v_lshl_add_u64 v[136:137], v[6:7], 0, s[62:63]
	v_or3_b32 v4, v4, s64, v28
	s_mov_b64 s[62:63], 0xb000020
	v_add_u32_e32 v27, 0, v26
	v_add_u32_e32 v19, 0, v19
	v_lshlrev_b32_e32 v18, 4, v18
	v_add_u32_e32 v3, 0, v3
	v_mul_u32_u24_e32 v44, 0x188, v140
	v_writelane_b32 v254, s77, 60
	v_lshl_add_u64 v[138:139], v[4:5], 0, s[62:63]
	s_movk_i32 s62, 0x6c00
	v_cmp_lt_i32_e64 s[6:7], -1, v10
	v_cmp_lt_i32_e64 s[8:9], -1, v14
	v_writelane_b32 v254, s3, 61
	s_mov_b64 s[76:77], 0
	v_add_u32_e32 v142, v27, v31
	v_add_u32_e32 v143, v27, v32
	v_add_u32_e32 v144, v27, v30
	v_add3_u32 v145, v19, v18, s62
	v_add3_u32 v146, v33, v34, s62
	v_add3_u32 v147, v3, v35, s62
	v_add_u32_e32 v148, v29, v36
	v_add_u32_e32 v149, v29, v37
	v_add_u32_e32 v150, v29, v38
	v_add_u32_e32 v151, v29, v39
	v_add_u32_e32 v152, v29, v40
	v_mbcnt_hi_u32_b32 v1, -1, v1
	v_add_u32_e32 v153, v43, v44
	v_add_u32_e32 v154, v41, v44
	v_add_u32_e32 v155, v42, v44
	v_add_u32_e32 v156, v45, v44
	v_add_u32_e32 v157, v46, v44
	s_mov_b64 s[78:79], 0x200000
	s_mov_b64 s[90:91], 0x80
	v_mov_b32_e32 v158, 0xff800000
	v_mov_b32_e32 v159, 0
	s_mov_b32 s3, 0x3fb8aa3b
	v_readfirstlane_b32 vcc_lo, v0
	s_nop 3
	s_lshr_b32 vcc_lo, vcc_lo, 6
	s_cmp_ge_u32 vcc_lo, 4
	s_cbranch_scc0 .Lattn_prio_done
	s_setprio 1
.Lattn_prio_done:
	s_mov_b64 exec, s[0:1]
	v_lshl_add_u64 v[240:241], s[94:95], 0, v[130:131]
	global_load_dwordx4 v[200:203], v[240:241], off
	s_mov_b64 exec, s[6:7]
	v_lshl_add_u64 v[240:241], s[94:95], 0, v[132:133]
	global_load_dwordx4 v[204:207], v[240:241], off
	s_mov_b64 exec, s[8:9]
	v_lshl_add_u64 v[240:241], s[94:95], 0, v[134:135]
	global_load_dwordx4 v[208:211], v[240:241], off
	s_mov_b64 exec, s[10:11]
	v_lshl_add_u64 v[240:241], s[94:95], 0, v[124:125]
	global_load_dwordx4 v[212:215], v[240:241], off
	s_mov_b64 exec, s[12:13]
	v_lshl_add_u64 v[240:241], s[94:95], 0, v[126:127]
	global_load_dwordx4 v[216:219], v[240:241], off
	s_mov_b64 exec, s[14:15]
	v_lshl_add_u64 v[240:241], s[94:95], 0, v[128:129]
	global_load_dwordx4 v[220:223], v[240:241], off
	s_mov_b64 exec, -1
	v_lshl_add_u64 v[240:241], s[94:95], 0, v[138:139]
	global_load_dwordx4 v[224:227], v[240:241], off offset:-32
	global_load_dwordx4 v[228:231], v[240:241], off offset:-16
	global_load_dwordx4 v[232:235], v[240:241], off
	global_load_dwordx4 v[236:239], v[240:241], off offset:16
	s_add_u32 vcc_lo, s4, s76
	s_addc_u32 vcc_hi, s5, s77
	global_load_dword v242, v2, vcc
	s_waitcnt vmcnt(0)
	s_barrier
	s_branch .LBB0_656
